# GEMM pipeline fill de-serialised: second staging batch issued before the first counted wait (vmcnt(2)->vmcnt(8), wait+barrier moved behind the batch)
# speedup vs baseline: 1.0014x; 1.0014x over previous
.LBB0_97:
	s_sext_i32_i8 s34, s6
	s_and_b64 s[6:7], s[8:9], exec
	s_mov_b32 s6, 0x12100000
	s_cselect_b32 s6, s6, 0x16100000
	s_add_u32 s6, s30, s6
	v_lshrrev_b32_e32 v16, 1, v0
	s_addc_u32 s7, s31, 0
	v_and_b32_e32 v16, 24, v16
	s_lshl_b32 s18, s13, 5
	v_and_b32_e32 v146, 15, v0
	v_lshlrev_b32_e32 v17, 1, v16
	v_lshlrev_b32_e32 v0, 2, v0
	s_and_b32 s64, s18, 0x60
	s_add_i32 m0, s15, 0x18000
	v_lshl_add_u64 v[8:9], v[8:9], 0, s[4:5]
	s_lshl_b32 s63, s16, 6
	v_lshl_or_b32 v17, v146, 6, v17
	s_lshl_b32 s16, s16, 13
	v_and_b32_e32 v0, 32, v0
	s_lshl_b32 s13, s64, 7
	global_load_lds_dwordx4 v[8:9], off
	v_lshl_add_u64 v[6:7], v[6:7], 0, s[4:5]
	s_add_i32 m0, s15, 0x1a000
	s_add_i32 s65, s15, 0x8000
	s_add_i32 s66, s15, 0xa000
	v_bitop3_b32 v18, v17, s16, v0 bitop3:0xde
	global_load_lds_dwordx4 v[6:7], off
	v_lshl_add_u64 v[2:3], v[2:3], 0, s[4:5]
	s_mov_b32 m0, s65
	s_add_u32 s16, s28, 0x40080
	global_load_lds_dwordx4 v[2:3], off
	v_lshl_add_u64 v[2:3], v[4:5], 0, s[4:5]
	s_mov_b32 m0, s66
	s_addc_u32 s17, s29, 0
	global_load_lds_dwordx4 v[2:3], off
	s_add_i32 m0, s15, 0x1c000
	v_lshl_add_u64 v[2:3], s[16:17], 0, v[134:135]
	global_load_lds_dwordx4 v[2:3], off
	v_lshl_add_u64 v[2:3], s[16:17], 0, v[130:131]
	s_add_i32 m0, s15, 0x1e000
	v_bitop3_b32 v147, v17, s13, v0 bitop3:0xde
	global_load_lds_dwordx4 v[2:3], off
	s_waitcnt vmcnt(8)
	s_barrier
	v_and_or_b32 v0, s18, 32, v16
	v_lshlrev_b32_e32 v0, 1, v0
	v_lshl_add_u64 v[138:139], s[6:7], 0, v[0:1]
	v_lshlrev_b32_e32 v0, 14, v14
	v_and_b32_e32 v0, 0xffff8000, v0
	v_lshl_add_u32 v0, v13, 11, v0
	v_and_b32_e32 v2, 1, v14
	v_lshl_or_b32 v0, v2, 6, v0
	v_lshl_add_u32 v140, v15, 1, v0
	v_lshlrev_b32_e32 v0, 14, v10
	v_and_b32_e32 v0, 0xffff8000, v0
	s_waitcnt vmcnt(6)
	v_lshl_add_u32 v0, v11, 11, v0
	v_and_b32_e32 v2, 1, v10
	s_cmpk_lt_u32 s12, 0x100
	v_lshl_or_b32 v0, v2, 6, v0
	s_mov_b32 s62, 0
	s_cselect_b64 s[12:13], -1, 0
	v_mov_b32_e32 v141, v1
	v_lshl_add_u32 v142, v12, 1, v0
	v_mov_b32_e32 v143, v1
	v_add_u32_e32 v148, 0, v18
	v_mov_b64_e32 v[144:145], s[0:1]
	s_barrier
	s_branch .LBB0_100

.LBB0_239:
	v_lshrrev_b32_e32 v17, 1, v15
	v_and_b32_e32 v17, 24, v17
	v_and_b32_e32 v16, 15, v15
	v_lshlrev_b32_e32 v18, 1, v17
	v_lshlrev_b32_e32 v15, 2, v15
	s_lshl_b32 s7, s7, 5
	v_lshl_or_b32 v156, s12, 6, v16
	v_lshl_or_b32 v16, v16, 6, v18
	s_lshl_b32 s12, s12, 13
	v_and_b32_e32 v15, 32, v15
	s_and_b32 s7, s7, 0x60
	s_add_i32 m0, s40, 0x18000
	v_lshl_add_u64 v[8:9], v[8:9], 0, s[4:5]
	v_bitop3_b32 v18, v16, s12, v15 bitop3:0xde
	s_lshl_b32 s12, s7, 7
	global_load_lds_dwordx4 v[8:9], off
	v_lshl_add_u64 v[6:7], v[6:7], 0, s[4:5]
	s_add_i32 m0, s40, 0x1a000
	s_add_i32 s52, s40, 0x8000
	s_add_i32 s53, s40, 0xa000
	v_bitop3_b32 v157, v16, s12, v15 bitop3:0xde
	global_load_lds_dwordx4 v[6:7], off
	v_lshl_add_u64 v[2:3], v[2:3], 0, s[4:5]
	s_mov_b32 m0, s52
	s_add_u32 s12, s28, 0x40080
	global_load_lds_dwordx4 v[2:3], off
	v_lshl_add_u64 v[2:3], v[4:5], 0, s[4:5]
	s_mov_b32 m0, s53
	s_addc_u32 s13, s29, 0
	global_load_lds_dwordx4 v[2:3], off
	s_add_i32 m0, s40, 0x1c000
	v_lshl_add_u64 v[2:3], s[12:13], 0, v[142:143]
	global_load_lds_dwordx4 v[2:3], off
	v_lshl_add_u64 v[2:3], s[12:13], 0, v[138:139]
	s_add_i32 m0, s40, 0x1e000
	v_readlane_b32 s56, v253, 40
	global_load_lds_dwordx4 v[2:3], off
	s_waitcnt vmcnt(8)
	s_barrier
	v_lshlrev_b32_e32 v2, 14, v13
	v_and_b32_e32 v2, 0xffff8000, v2
	v_lshl_add_u32 v2, v12, 11, v2
	v_and_b32_e32 v3, 1, v13
	v_lshl_or_b32 v2, v3, 6, v2
	s_cmpk_lt_u32 s6, 0x100
	v_readlane_b32 s66, v253, 50
	v_lshl_add_u32 v146, v14, 1, v2
	v_lshlrev_b32_e32 v2, 14, v0
	s_cselect_b64 s[12:13], -1, 0
	v_readlane_b32 s67, v253, 51
	s_add_u32 s14, s66, 0x1000
	v_and_b32_e32 v2, 0xffff8000, v2
	s_waitcnt vmcnt(6)
	s_addc_u32 s15, s67, 0
	v_lshl_add_u32 v2, v10, 11, v2
	v_and_b32_e32 v0, 1, v0
	s_add_u32 s16, s30, 0x16c00000
	v_or_b32_e32 v158, s7, v17
	v_lshl_or_b32 v0, v0, 6, v2
	v_readlane_b32 s6, v253, 13
	s_addc_u32 s17, s31, 0
	v_mov_b32_e32 v147, v1
	v_lshl_add_u32 v148, v11, 1, v0
	v_mov_b32_e32 v149, v1
	s_mov_b32 s54, 0
	v_add_u32_e32 v159, 0, v18
	v_readlane_b32 s34, v252, 35
	s_mov_b32 s35, s6
	s_barrier
	v_readlane_b32 s57, v253, 41
	v_readlane_b32 s58, v253, 42
	v_readlane_b32 s59, v253, 43
	v_readlane_b32 s60, v253, 44
	v_readlane_b32 s61, v253, 45
	v_readlane_b32 s62, v253, 46
	v_readlane_b32 s63, v253, 47
	v_readlane_b32 s64, v253, 48
	v_readlane_b32 s65, v253, 49
	v_readlane_b32 s68, v253, 52
	v_readlane_b32 s69, v253, 53
	v_readlane_b32 s70, v253, 54
	v_readlane_b32 s71, v253, 55
	v_readlane_b32 s7, v253, 14
	s_branch .LBB0_242

.LBB0_514:
	v_readlane_b32 s90, v254, 35
	v_readlane_b32 s91, v254, 36
	v_mov_b32_e32 v131, v1
	v_mov_b32_e32 v135, v1
	v_lshl_add_u64 v[10:11], s[90:91], 0, v[0:1]
	v_lshl_add_u64 v[12:13], s[90:91], 0, v[130:131]
	s_add_i32 m0, s14, 0x18000
	v_lshl_add_u64 v[10:11], v[10:11], 0, s[4:5]
	v_lshl_add_u64 v[18:19], s[88:89], 0, v[134:135]
	v_mov_b32_e32 v133, v1
	global_load_lds_dwordx4 v[10:11], off
	v_lshl_add_u64 v[10:11], v[12:13], 0, s[4:5]
	s_add_i32 m0, s14, 0x1a000
	s_add_i32 s35, s14, 0x8000
	v_lshl_add_u64 v[14:15], s[28:29], 0, v[0:1]
	v_lshl_add_u64 v[16:17], s[28:29], 0, v[130:131]
	v_lshl_add_u64 v[20:21], s[88:89], 0, v[132:133]
	global_load_lds_dwordx4 v[10:11], off
	v_lshl_add_u64 v[10:11], v[18:19], 0, s[4:5]
	s_mov_b32 m0, s35
	s_add_i32 s28, s14, 0xa000
	global_load_lds_dwordx4 v[10:11], off
	v_lshl_add_u64 v[10:11], v[20:21], 0, s[4:5]
	s_mov_b32 m0, s28
	v_bfe_u32 v144, v2, 4, 2
	global_load_lds_dwordx4 v[10:11], off
	s_add_i32 m0, s14, 0x1c000
	v_lshl_add_u64 v[10:11], v[14:15], 0, s[4:5]
	global_load_lds_dwordx4 v[10:11], off
	v_lshl_add_u64 v[10:11], v[16:17], 0, s[4:5]
	s_add_i32 m0, s14, 0x1e000
	v_and_b32_e32 v9, 15, v2
	global_load_lds_dwordx4 v[10:11], off
	s_waitcnt vmcnt(8)
	s_barrier
	v_lshlrev_b32_e32 v10, 4, v144
	v_lshlrev_b32_e32 v2, 2, v2
	s_and_b32 s34, s7, 3
	v_lshl_or_b32 v145, s6, 6, v9
	v_lshl_or_b32 v9, v9, 6, v10
	s_lshl_b32 s6, s6, 13
	v_and_b32_e32 v2, 32, v2
	v_bitop3_b32 v10, v9, s6, v2 bitop3:0xde
	s_lshl_b32 s6, s34, 12
	v_bitop3_b32 v146, v9, s6, v2 bitop3:0xde
	v_add_u32_e32 v2, v8, v6
	v_add_lshl_u32 v6, v2, v7, 1
	v_readlane_b32 s6, v254, 37
	v_add_u32_e32 v2, v5, v3
	s_waitcnt vmcnt(6)
	v_mov_b32_e32 v7, v1
	v_readlane_b32 s7, v254, 38
	v_add_lshl_u32 v2, v2, v4, 1
	v_mov_b32_e32 v3, v1
	v_mov_b32_e32 v14, v1
	v_mov_b32_e32 v15, v1
	v_mov_b32_e32 v16, v1
	v_mov_b32_e32 v17, v1
	v_lshl_add_u64 v[136:137], s[6:7], 0, v[6:7]
	v_lshl_add_u64 v[138:139], s[6:7], 0, v[2:3]
	v_add_u32_e32 v147, 0, v10
	v_mov_b64_e32 v[10:11], v[14:15]
	v_mov_b64_e32 v[32:33], v[16:17]
	v_mov_b64_e32 v[28:29], v[16:17]
	v_mov_b64_e32 v[48:49], v[16:17]
	v_mov_b64_e32 v[44:45], v[16:17]
	v_mov_b64_e32 v[64:65], v[16:17]
	v_mov_b64_e32 v[60:61], v[16:17]
	v_mov_b64_e32 v[2:3], v[14:15]
	v_mov_b64_e32 v[6:7], v[14:15]
	v_mov_b64_e32 v[20:21], v[16:17]
	v_mov_b64_e32 v[24:25], v[16:17]
	v_mov_b64_e32 v[36:37], v[16:17]
	v_mov_b64_e32 v[40:41], v[16:17]
	v_mov_b64_e32 v[52:53], v[16:17]
	v_mov_b64_e32 v[56:57], v[16:17]
	v_mov_b64_e32 v[80:81], v[16:17]
	v_mov_b64_e32 v[76:77], v[16:17]
	v_mov_b64_e32 v[96:97], v[16:17]
	v_mov_b64_e32 v[92:93], v[16:17]
	v_mov_b64_e32 v[100:101], v[16:17]
	v_mov_b64_e32 v[104:105], v[16:17]
	v_mov_b64_e32 v[116:117], v[16:17]
	v_mov_b64_e32 v[120:121], v[16:17]
	v_mov_b64_e32 v[68:69], v[16:17]
	v_mov_b64_e32 v[72:73], v[16:17]
	v_mov_b64_e32 v[84:85], v[16:17]
	v_mov_b64_e32 v[88:89], v[16:17]
	v_mov_b64_e32 v[108:109], v[16:17]
	v_mov_b64_e32 v[112:113], v[16:17]
	v_mov_b64_e32 v[124:125], v[16:17]
	v_mov_b64_e32 v[128:129], v[16:17]
	s_mov_b32 s29, 0
	v_mov_b64_e32 v[12:13], v[16:17]
	v_mov_b64_e32 v[30:31], v[14:15]
	v_mov_b64_e32 v[26:27], v[14:15]
	v_mov_b64_e32 v[46:47], v[14:15]
	v_mov_b64_e32 v[42:43], v[14:15]
	v_mov_b64_e32 v[62:63], v[14:15]
	v_mov_b64_e32 v[58:59], v[14:15]
	v_mov_b64_e32 v[4:5], v[16:17]
	v_mov_b64_e32 v[8:9], v[16:17]
	v_mov_b64_e32 v[18:19], v[14:15]
	v_mov_b64_e32 v[22:23], v[14:15]
	v_mov_b64_e32 v[34:35], v[14:15]
	v_mov_b64_e32 v[38:39], v[14:15]
	v_mov_b64_e32 v[50:51], v[14:15]
	v_mov_b64_e32 v[54:55], v[14:15]
	v_mov_b64_e32 v[78:79], v[14:15]
	v_mov_b64_e32 v[74:75], v[14:15]
	v_mov_b64_e32 v[94:95], v[14:15]
	v_mov_b64_e32 v[90:91], v[14:15]
	v_mov_b64_e32 v[98:99], v[14:15]
	v_mov_b64_e32 v[102:103], v[14:15]
	v_mov_b64_e32 v[114:115], v[14:15]
	v_mov_b64_e32 v[118:119], v[14:15]
	v_mov_b64_e32 v[66:67], v[14:15]
	v_mov_b64_e32 v[70:71], v[14:15]
	v_mov_b64_e32 v[82:83], v[14:15]
	v_mov_b64_e32 v[86:87], v[14:15]
	v_mov_b64_e32 v[106:107], v[14:15]
	v_mov_b64_e32 v[110:111], v[14:15]
	v_mov_b64_e32 v[122:123], v[14:15]
	v_mov_b64_e32 v[126:127], v[14:15]
	v_readlane_b32 s84, v252, 37
	v_readlane_b32 s81, v252, 36
	s_barrier
	s_branch .LBB0_516

.LBB0_646:
	v_lshrrev_b32_e32 v22, 1, v8
	v_and_b32_e32 v22, 24, v22
	v_mov_b32_e32 v131, v1
	v_and_b32_e32 v9, 15, v8
	v_lshlrev_b32_e32 v23, 1, v22
	v_lshlrev_b32_e32 v8, 2, v8
	v_lshl_add_u64 v[14:15], s[6:7], 0, v[0:1]
	v_lshl_add_u64 v[16:17], s[6:7], 0, v[130:131]
	v_lshl_or_b32 v146, s14, 6, v9
	v_lshl_or_b32 v9, v9, 6, v23
	s_lshl_b32 s6, s14, 13
	v_and_b32_e32 v8, 32, v8
	v_bitop3_b32 v23, v9, s6, v8 bitop3:0xde
	s_lshl_b32 s6, s9, 5
	s_and_b32 s6, s6, 0x60
	v_lshl_add_u64 v[10:11], s[36:37], 0, v[0:1]
	s_lshl_b32 s7, s6, 7
	v_lshl_add_u64 v[12:13], s[36:37], 0, v[130:131]
	v_mov_b32_e32 v135, v1
	v_bitop3_b32 v147, v9, s7, v8 bitop3:0xde
	s_add_i32 m0, s40, 0x18000
	v_lshl_add_u64 v[8:9], v[10:11], 0, s[4:5]
	v_lshl_add_u64 v[18:19], s[28:29], 0, v[134:135]
	v_mov_b32_e32 v133, v1
	global_load_lds_dwordx4 v[8:9], off
	v_lshl_add_u64 v[8:9], v[12:13], 0, s[4:5]
	s_add_i32 m0, s40, 0x1a000
	s_add_i32 s48, s40, 0x8000
	v_lshl_add_u64 v[20:21], s[28:29], 0, v[132:133]
	global_load_lds_dwordx4 v[8:9], off
	v_lshl_add_u64 v[8:9], v[18:19], 0, s[4:5]
	s_mov_b32 m0, s48
	s_add_i32 s49, s40, 0xa000
	global_load_lds_dwordx4 v[8:9], off
	v_lshl_add_u64 v[8:9], v[20:21], 0, s[4:5]
	s_mov_b32 m0, s49
	s_lshr_b32 s47, s79, 6
	global_load_lds_dwordx4 v[8:9], off
	s_add_i32 m0, s40, 0x1c000
	v_lshl_add_u64 v[8:9], v[14:15], 0, s[4:5]
	global_load_lds_dwordx4 v[8:9], off
	v_lshl_add_u64 v[8:9], v[16:17], 0, s[4:5]
	s_add_i32 m0, s40, 0x1e000
	s_add_i32 s50, s47, -2
	global_load_lds_dwordx4 v[8:9], off
	s_waitcnt vmcnt(8)
	s_barrier
	s_waitcnt vmcnt(6)
	v_add_u32_e32 v5, v7, v5
	v_add_u32_e32 v2, v4, v2
	s_cmpk_lt_u32 s8, 0x100
	v_add_lshl_u32 v6, v5, v6, 1
	v_mov_b32_e32 v7, v1
	v_add_lshl_u32 v2, v2, v3, 1
	v_mov_b32_e32 v3, v1
	s_cselect_b64 s[20:21], -1, 0
	s_mov_b32 s19, s18
	s_mov_b32 s22, s18
	s_mov_b32 s23, s18
	v_or_b32_e32 v148, s6, v22
	v_lshl_add_u64 v[136:137], s[0:1], 0, v[6:7]
	v_lshl_add_u64 v[138:139], s[0:1], 0, v[2:3]
	s_mov_b32 s51, 0
	v_add_u32_e32 v149, 0, v23
	v_readlane_b32 s14, v252, 42
	v_readlane_b32 s15, v252, 41
	s_barrier
	s_branch .LBB0_649

.LBB0_678:
	v_lshl_add_u64 v[10:11], s[22:23], 0, v[0:1]
	v_mov_b32_e32 v131, v1
	s_lshl_b32 s7, s7, 5
	v_lshl_add_u64 v[12:13], s[22:23], 0, v[130:131]
	v_mov_b32_e32 v135, v1
	s_and_b32 s7, s7, 0x60
	s_add_i32 m0, s36, 0x18000
	v_lshl_add_u64 v[10:11], v[10:11], 0, s[4:5]
	v_lshl_add_u64 v[14:15], s[20:21], 0, v[134:135]
	v_mov_b32_e32 v133, v1
	s_lshl_b32 s11, s6, 13
	s_lshl_b32 s14, s7, 7
	global_load_lds_dwordx4 v[10:11], off
	v_lshl_add_u64 v[10:11], v[12:13], 0, s[4:5]
	s_add_i32 m0, s36, 0x1a000
	s_add_i32 s40, s36, 0x8000
	s_add_i32 s41, s36, 0xa000
	v_lshl_add_u64 v[16:17], s[20:21], 0, v[132:133]
	global_load_lds_dwordx4 v[10:11], off
	v_lshl_add_u64 v[10:11], v[14:15], 0, s[4:5]
	s_mov_b32 m0, s40
	s_add_u32 s12, s22, 0x40080
	global_load_lds_dwordx4 v[10:11], off
	v_lshl_add_u64 v[10:11], v[16:17], 0, s[4:5]
	s_mov_b32 m0, s41
	s_addc_u32 s13, s23, 0
	global_load_lds_dwordx4 v[10:11], off
	s_add_i32 m0, s36, 0x1c000
	v_lshl_add_u64 v[10:11], s[12:13], 0, v[0:1]
	global_load_lds_dwordx4 v[10:11], off
	v_lshl_add_u64 v[10:11], s[12:13], 0, v[130:131]
	s_add_i32 m0, s36, 0x1e000
	v_and_b32_e32 v9, 15, v2
	global_load_lds_dwordx4 v[10:11], off
	s_waitcnt vmcnt(8)
	s_barrier
	v_lshrrev_b32_e32 v10, 1, v2
	v_and_b32_e32 v10, 24, v10
	v_lshlrev_b32_e32 v11, 1, v10
	v_lshlrev_b32_e32 v2, 2, v2
	v_lshl_or_b32 v142, s6, 6, v9
	v_lshl_or_b32 v9, v9, 6, v11
	v_and_b32_e32 v2, 32, v2
	v_bitop3_b32 v11, v9, s11, v2 bitop3:0xde
	v_bitop3_b32 v143, v9, s14, v2 bitop3:0xde
	v_lshlrev_b32_e32 v2, 14, v7
	v_and_b32_e32 v2, 0xffff8000, v2
	v_lshl_add_u32 v2, v6, 11, v2
	v_and_b32_e32 v6, 1, v7
	v_lshl_or_b32 v2, v6, 6, v2
	v_lshl_add_u32 v136, v8, 1, v2
	v_lshlrev_b32_e32 v2, 14, v3
	v_and_b32_e32 v2, 0xffff8000, v2
	s_waitcnt vmcnt(6)
	v_lshl_add_u32 v2, v4, 11, v2
	v_and_b32_e32 v3, 1, v3
	s_cmpk_lt_u32 s10, 0x100
	v_or_b32_e32 v144, s7, v10
	v_lshl_or_b32 v2, v3, 6, v2
	v_readlane_b32 s6, v252, 28
	s_cselect_b64 s[10:11], -1, 0
	v_mov_b32_e32 v137, v1
	v_lshl_add_u32 v138, v5, 1, v2
	v_mov_b32_e32 v139, v1
	s_mov_b32 s42, 0
	v_add_u32_e32 v145, 0, v11
	v_readlane_b32 s34, v252, 27
	s_mov_b32 s35, s6
	s_barrier
	v_readlane_b32 s7, v252, 29
	s_branch .LBB0_681
